# v31 + short-conv phase: all 32 row loads of a thread's 16-row chunk issued up front with counted waits (was one exposed memory latency per row)
# baseline (speedup 1.0000x reference)
; __device__ __forceinline__ float bf_lo(unsigned u) { return __uint_as_float(u << 16); }
; __device__ __forceinline__ float bf_hi(unsigned u) { return __uint_as_float(u & 0xffff0000u); }
; __device__ __forceinline__ void conv_phase(const bf16_t* proj, bf16_t* ycat, const float* cw, const float* cb, int tid) {
;     ...
; #pragma unroll 4
;         for (int rr = 0; rr < 16; ++rr) {
;             const bf16_t* p = proj + (size_t)(row0 + rr) * 1024 + c0;
;             const u32x4 gb = *(const u32x4*)p, pc = *(const u32x4*)(p + 512);
;             float p0[8], y[8];
; #pragma unroll
;             for (int e = 0; e < 4; ++e) { p0[2 * e] = bf_lo(pc[e]); p0[2 * e + 1] = bf_hi(pc[e]); }
; #pragma unroll
;             for (int e = 0; e < 8; ++e) y[e] = w2[e] * p0[e] + w1[e] * p1[e] + w0[e] * p2[e] + bb[e];
;             u32x4 o;
; #pragma unroll
;             for (int e = 0; e < 4; ++e) o[e] = cvt_pk_bf16(bf_lo(gb[e]) * y[2 * e], bf_hi(gb[e]) * y[2 * e + 1]);
;             *(u32x4*)(ycat + (size_t)(row0 + rr) * DM + AW + c0) = o;
; #pragma unroll
;             for (int e = 0; e < 8; ++e) { p2[e] = p1[e]; p1[e] = p0[e]; }
;         }
.LBB0_288:
	v_mov_b32_e32 v75, 0
	v_mov_b32_e32 v74, v69
	v_lshl_add_u64 v[166:167], v[74:75], 1, v[36:37]
	global_load_dwordx4 v[76:79], v[166:167], off
	global_load_dwordx4 v[80:83], v[166:167], off offset:1024
	v_add_u32_e32 v74, 0x400, v69
	v_lshl_add_u64 v[166:167], v[74:75], 1, v[36:37]
	global_load_dwordx4 v[84:87], v[166:167], off
	global_load_dwordx4 v[88:91], v[166:167], off offset:1024
	v_add_u32_e32 v74, 0x800, v69
	v_lshl_add_u64 v[166:167], v[74:75], 1, v[36:37]
	global_load_dwordx4 v[92:95], v[166:167], off
	global_load_dwordx4 v[96:99], v[166:167], off offset:1024
	v_add_u32_e32 v74, 0xc00, v69
	v_lshl_add_u64 v[166:167], v[74:75], 1, v[36:37]
	global_load_dwordx4 v[100:103], v[166:167], off
	global_load_dwordx4 v[104:107], v[166:167], off offset:1024
	v_add_u32_e32 v74, 0x1000, v69
	v_lshl_add_u64 v[166:167], v[74:75], 1, v[36:37]
	global_load_dwordx4 v[108:111], v[166:167], off
	global_load_dwordx4 v[112:115], v[166:167], off offset:1024
	v_add_u32_e32 v74, 0x1400, v69
	v_lshl_add_u64 v[166:167], v[74:75], 1, v[36:37]
	global_load_dwordx4 v[116:119], v[166:167], off
	global_load_dwordx4 v[120:123], v[166:167], off offset:1024
	v_add_u32_e32 v74, 0x1800, v69
	v_lshl_add_u64 v[166:167], v[74:75], 1, v[36:37]
	global_load_dwordx4 v[124:127], v[166:167], off
	global_load_dwordx4 v[128:131], v[166:167], off offset:1024
	v_add_u32_e32 v74, 0x1c00, v69
	v_lshl_add_u64 v[166:167], v[74:75], 1, v[36:37]
	global_load_dwordx4 v[132:135], v[166:167], off
	global_load_dwordx4 v[138:141], v[166:167], off offset:1024
	v_add_u32_e32 v74, 0x2000, v69
	v_lshl_add_u64 v[166:167], v[74:75], 1, v[36:37]
	global_load_dwordx4 v[142:145], v[166:167], off
	global_load_dwordx4 v[146:149], v[166:167], off offset:1024
	v_add_u32_e32 v74, 0x2400, v69
	v_lshl_add_u64 v[166:167], v[74:75], 1, v[36:37]
	global_load_dwordx4 v[150:153], v[166:167], off
	global_load_dwordx4 v[154:157], v[166:167], off offset:1024
	v_add_u32_e32 v74, 0x2800, v69
	v_lshl_add_u64 v[166:167], v[74:75], 1, v[36:37]
	global_load_dwordx4 v[158:161], v[166:167], off
	global_load_dwordx4 v[162:165], v[166:167], off offset:1024
	v_add_u32_e32 v74, 0x2c00, v69
	v_lshl_add_u64 v[166:167], v[74:75], 1, v[36:37]
	global_load_dwordx4 v[186:189], v[166:167], off
	global_load_dwordx4 v[190:193], v[166:167], off offset:1024
	v_add_u32_e32 v74, 0x3000, v69
	v_lshl_add_u64 v[166:167], v[74:75], 1, v[36:37]
	global_load_dwordx4 v[194:197], v[166:167], off
	global_load_dwordx4 v[198:201], v[166:167], off offset:1024
	v_add_u32_e32 v74, 0x3400, v69
	v_lshl_add_u64 v[166:167], v[74:75], 1, v[36:37]
	global_load_dwordx4 v[202:205], v[166:167], off
	global_load_dwordx4 v[206:209], v[166:167], off offset:1024
	v_add_u32_e32 v74, 0x3800, v69
	v_lshl_add_u64 v[166:167], v[74:75], 1, v[36:37]
	global_load_dwordx4 v[210:213], v[166:167], off
	global_load_dwordx4 v[214:217], v[166:167], off offset:1024
	v_add_u32_e32 v74, 0x3c00, v69
	v_lshl_add_u64 v[166:167], v[74:75], 1, v[36:37]
	global_load_dwordx4 v[218:221], v[166:167], off
	global_load_dwordx4 v[230:233], v[166:167], off offset:1024
	v_add_u32_e32 v168, s4, v69
	v_lshlrev_b64 v[70:71], 1, v[168:169]
	v_lshl_add_u64 v[44:45], v[36:37], 0, v[70:71]
	s_waitcnt vmcnt(30)
	v_mov_b32_e32 v40, v76
	v_mov_b32_e32 v41, v77
	v_mov_b32_e32 v42, v78
	v_mov_b32_e32 v43, v79
	v_mov_b32_e32 v44, v80
	v_mov_b32_e32 v45, v81
	v_mov_b32_e32 v46, v82
	v_mov_b32_e32 v47, v83
	s_addk_i32 s4, 0x1000
	v_lshlrev_b32_e32 v60, 16, v44
	v_and_b32_e32 v61, 0xffff0000, v44
	v_pk_mul_f32 v[54:55], v[16:17], v[60:61]
	v_lshlrev_b32_e32 v58, 16, v45
	v_pk_fma_f32 v[54:55], v[12:13], v[34:35], v[54:55]
	v_and_b32_e32 v59, 0xffff0000, v45
	v_pk_fma_f32 v[48:49], v[4:5], v[48:49], v[54:55]
	v_pk_mul_f32 v[44:45], v[18:19], v[58:59]
	v_pk_add_f32 v[48:49], v[28:29], v[48:49]
	v_lshlrev_b32_e32 v54, 16, v40
	v_and_b32_e32 v55, 0xffff0000, v40
	v_pk_fma_f32 v[44:45], v[14:15], v[62:63], v[44:45]
	v_pk_mul_f32 v[48:49], v[48:49], v[54:55]
	v_pk_fma_f32 v[44:45], v[6:7], v[50:51], v[44:45]
	v_cvt_pk_bf16_f32 v40, v48, v49
	v_pk_add_f32 v[44:45], v[30:31], v[44:45]
	v_lshlrev_b32_e32 v48, 16, v41
	v_and_b32_e32 v49, 0xffff0000, v41
	v_pk_mul_f32 v[44:45], v[44:45], v[48:49]
	v_lshlrev_b32_e32 v56, 16, v46
	v_and_b32_e32 v57, 0xffff0000, v46
	v_cvt_pk_bf16_f32 v41, v44, v45
	v_pk_mul_f32 v[44:45], v[20:21], v[56:57]
	v_lshlrev_b32_e32 v54, 16, v47
	v_pk_fma_f32 v[44:45], v[8:9], v[64:65], v[44:45]
	v_and_b32_e32 v55, 0xffff0000, v47
	v_pk_fma_f32 v[32:33], v[0:1], v[32:33], v[44:45]
	v_lshlrev_b32_e32 v44, 16, v42
	v_pk_add_f32 v[32:33], v[24:25], v[32:33]
	v_and_b32_e32 v45, 0xffff0000, v42
	v_pk_mul_f32 v[32:33], v[32:33], v[44:45]
	v_lshlrev_b32_e32 v44, 16, v43
	v_cvt_pk_bf16_f32 v42, v32, v33
	v_pk_mul_f32 v[32:33], v[22:23], v[54:55]
	v_and_b32_e32 v45, 0xffff0000, v43
	v_pk_fma_f32 v[32:33], v[10:11], v[66:67], v[32:33]
	s_nop 0
	v_pk_fma_f32 v[32:33], v[2:3], v[52:53], v[32:33]
	s_nop 0
	v_pk_add_f32 v[32:33], v[26:27], v[32:33]
	s_nop 0
	v_pk_mul_f32 v[32:33], v[32:33], v[44:45]
	s_nop 0
	v_cvt_pk_bf16_f32 v43, v32, v33
	v_lshl_add_u64 v[32:33], v[38:39], 0, v[70:71]
	global_store_dwordx4 v[32:33], v[40:43], off offset:1024
	v_add_u32_e32 v32, 0x400, v168
	v_mov_b32_e32 v33, v169
	v_lshlrev_b64 v[52:53], 1, v[32:33]
	v_lshl_add_u64 v[32:33], v[36:37], 0, v[52:53]
	s_waitcnt vmcnt(29)
; __device__ __forceinline__ float bf_lo(unsigned u) { return __uint_as_float(u << 16); }
; __device__ __forceinline__ float bf_hi(unsigned u) { return __uint_as_float(u & 0xffff0000u); }
; __device__ __forceinline__ void conv_phase(const bf16_t* proj, bf16_t* ycat, const float* cw, const float* cb, int tid) {
;     ...
; #pragma unroll 4
;         for (int rr = 0; rr < 16; ++rr) {
;             const bf16_t* p = proj + (size_t)(row0 + rr) * 1024 + c0;
;             const u32x4 gb = *(const u32x4*)p, pc = *(const u32x4*)(p + 512);
;             float p0[8], y[8];
; #pragma unroll
;             for (int e = 0; e < 4; ++e) { p0[2 * e] = bf_lo(pc[e]); p0[2 * e + 1] = bf_hi(pc[e]); }
; #pragma unroll
;             for (int e = 0; e < 8; ++e) y[e] = w2[e] * p0[e] + w1[e] * p1[e] + w0[e] * p2[e] + bb[e];
;             u32x4 o;
; #pragma unroll
;             for (int e = 0; e < 4; ++e) o[e] = cvt_pk_bf16(bf_lo(gb[e]) * y[2 * e], bf_hi(gb[e]) * y[2 * e + 1]);
;             *(u32x4*)(ycat + (size_t)(row0 + rr) * DM + AW + c0) = o;
; #pragma unroll
;             for (int e = 0; e < 8; ++e) { p2[e] = p1[e]; p1[e] = p0[e]; }
;         }
	v_mov_b32_e32 v48, v84
	v_mov_b32_e32 v49, v85
	v_mov_b32_e32 v50, v86
	v_mov_b32_e32 v51, v87
	v_mov_b32_e32 v70, v88
	v_mov_b32_e32 v71, v89
	v_mov_b32_e32 v72, v90
	v_mov_b32_e32 v73, v91
	v_lshlrev_b32_e32 v40, 16, v49
	v_lshlrev_b32_e32 v46, 16, v70
	v_and_b32_e32 v47, 0xffff0000, v70
	v_pk_mul_f32 v[32:33], v[16:17], v[46:47]
	v_lshlrev_b32_e32 v44, 16, v71
	v_pk_fma_f32 v[32:33], v[12:13], v[60:61], v[32:33]
	v_and_b32_e32 v45, 0xffff0000, v71
	v_pk_fma_f32 v[32:33], v[4:5], v[34:35], v[32:33]
	v_lshlrev_b32_e32 v34, 16, v48
	v_pk_add_f32 v[32:33], v[28:29], v[32:33]
	v_and_b32_e32 v35, 0xffff0000, v48
	v_pk_mul_f32 v[32:33], v[32:33], v[34:35]
	v_pk_mul_f32 v[34:35], v[18:19], v[44:45]
	v_and_b32_e32 v41, 0xffff0000, v49
	v_pk_fma_f32 v[34:35], v[14:15], v[58:59], v[34:35]
	v_lshlrev_b32_e32 v42, 16, v72
	v_pk_fma_f32 v[34:35], v[6:7], v[62:63], v[34:35]
	v_and_b32_e32 v43, 0xffff0000, v72
	v_pk_add_f32 v[34:35], v[30:31], v[34:35]
	v_cvt_pk_bf16_f32 v32, v32, v33
	v_pk_mul_f32 v[34:35], v[34:35], v[40:41]
	v_lshlrev_b32_e32 v40, 16, v50
	v_cvt_pk_bf16_f32 v33, v34, v35
	v_pk_mul_f32 v[34:35], v[20:21], v[42:43]
	v_and_b32_e32 v41, 0xffff0000, v50
	v_pk_fma_f32 v[34:35], v[8:9], v[56:57], v[34:35]
	v_lshlrev_b32_e32 v50, 16, v51
	v_pk_fma_f32 v[34:35], v[0:1], v[64:65], v[34:35]
	v_and_b32_e32 v51, 0xffff0000, v51
	v_pk_add_f32 v[34:35], v[24:25], v[34:35]
	s_nop 0
	v_pk_mul_f32 v[34:35], v[34:35], v[40:41]
	v_lshlrev_b32_e32 v40, 16, v73
	v_and_b32_e32 v41, 0xffff0000, v73
	v_pk_mul_f32 v[48:49], v[22:23], v[40:41]
	v_cvt_pk_bf16_f32 v34, v34, v35
	v_pk_fma_f32 v[48:49], v[10:11], v[54:55], v[48:49]
	s_nop 0
	v_pk_fma_f32 v[48:49], v[2:3], v[66:67], v[48:49]
	s_nop 0
	v_pk_add_f32 v[48:49], v[26:27], v[48:49]
	s_nop 0
	v_pk_mul_f32 v[48:49], v[48:49], v[50:51]
	s_nop 0
	v_cvt_pk_bf16_f32 v35, v48, v49
	v_lshl_add_u64 v[48:49], v[38:39], 0, v[52:53]
	global_store_dwordx4 v[48:49], v[32:35], off offset:1024
	s_nop 1
	v_add_u32_e32 v32, 0x800, v168
	v_mov_b32_e32 v33, v169
	v_lshlrev_b64 v[62:63], 1, v[32:33]
	v_lshl_add_u64 v[48:49], v[36:37], 0, v[62:63]
	s_waitcnt vmcnt(28)
	v_mov_b32_e32 v32, v92
	v_mov_b32_e32 v33, v93
	v_mov_b32_e32 v34, v94
	v_mov_b32_e32 v35, v95
	v_mov_b32_e32 v50, v96
	v_mov_b32_e32 v51, v97
	v_mov_b32_e32 v52, v98
	v_mov_b32_e32 v53, v99
	v_add_u32_e32 v168, 0xc00, v168
	v_lshlrev_b64 v[70:71], 1, v[168:169]
	v_lshlrev_b32_e32 v48, 16, v50
	v_and_b32_e32 v49, 0xffff0000, v50
	v_pk_mul_f32 v[64:65], v[16:17], v[48:49]
	v_lshlrev_b32_e32 v50, 16, v51
	v_pk_fma_f32 v[64:65], v[12:13], v[46:47], v[64:65]
	v_and_b32_e32 v51, 0xffff0000, v51
	v_pk_fma_f32 v[60:61], v[4:5], v[60:61], v[64:65]
	v_lshlrev_b32_e32 v64, 16, v32
	v_pk_add_f32 v[60:61], v[28:29], v[60:61]
	v_and_b32_e32 v65, 0xffff0000, v32
	v_pk_mul_f32 v[60:61], v[60:61], v[64:65]
	v_lshlrev_b32_e32 v32, 16, v33
	v_cvt_pk_bf16_f32 v64, v60, v61
	v_pk_mul_f32 v[60:61], v[18:19], v[50:51]
	v_and_b32_e32 v33, 0xffff0000, v33
	v_pk_fma_f32 v[60:61], v[14:15], v[44:45], v[60:61]
	s_nop 0
	v_pk_fma_f32 v[58:59], v[6:7], v[58:59], v[60:61]
	s_nop 0
	v_pk_add_f32 v[58:59], v[30:31], v[58:59]
	s_nop 0
	v_pk_mul_f32 v[32:33], v[58:59], v[32:33]
	s_nop 0
	v_cvt_pk_bf16_f32 v65, v32, v33
	v_lshlrev_b32_e32 v32, 16, v52
	v_and_b32_e32 v33, 0xffff0000, v52
	v_pk_mul_f32 v[58:59], v[20:21], v[32:33]
	v_lshlrev_b32_e32 v52, 16, v53
	v_pk_fma_f32 v[58:59], v[8:9], v[42:43], v[58:59]
	v_and_b32_e32 v53, 0xffff0000, v53
	v_pk_fma_f32 v[56:57], v[0:1], v[56:57], v[58:59]
	v_lshlrev_b32_e32 v58, 16, v34
	v_pk_add_f32 v[56:57], v[24:25], v[56:57]
	v_and_b32_e32 v59, 0xffff0000, v34
	v_pk_mul_f32 v[56:57], v[56:57], v[58:59]
	v_lshlrev_b32_e32 v34, 16, v35
	v_cvt_pk_bf16_f32 v66, v56, v57
	v_pk_mul_f32 v[56:57], v[22:23], v[52:53]
	v_and_b32_e32 v35, 0xffff0000, v35
	v_pk_fma_f32 v[56:57], v[10:11], v[40:41], v[56:57]
	s_nop 0
	v_pk_fma_f32 v[54:55], v[2:3], v[54:55], v[56:57]
	s_nop 0
	v_pk_add_f32 v[54:55], v[26:27], v[54:55]
	s_nop 0
	v_pk_mul_f32 v[34:35], v[54:55], v[34:35]
	s_nop 0
	v_cvt_pk_bf16_f32 v67, v34, v35
	v_lshl_add_u64 v[34:35], v[38:39], 0, v[62:63]
	global_store_dwordx4 v[34:35], v[64:67], off offset:1024
	v_lshl_add_u64 v[34:35], v[36:37], 0, v[70:71]
	s_waitcnt vmcnt(27)
	v_mov_b32_e32 v54, v100
	v_mov_b32_e32 v55, v101
	v_mov_b32_e32 v56, v102
	v_mov_b32_e32 v57, v103
	v_mov_b32_e32 v58, v104
	v_mov_b32_e32 v59, v105
	v_mov_b32_e32 v60, v106
	v_mov_b32_e32 v61, v107
	v_lshlrev_b32_e32 v34, 16, v58
	v_and_b32_e32 v35, 0xffff0000, v58
	v_pk_mul_f32 v[62:63], v[16:17], v[34:35]
	v_lshlrev_b32_e32 v64, 16, v60
	v_pk_fma_f32 v[62:63], v[12:13], v[48:49], v[62:63]
	v_and_b32_e32 v65, 0xffff0000, v60
	v_pk_fma_f32 v[46:47], v[4:5], v[46:47], v[62:63]
	v_lshlrev_b32_e32 v62, 16, v54
	v_pk_add_f32 v[46:47], v[28:29], v[46:47]
	v_and_b32_e32 v63, 0xffff0000, v54
	v_pk_mul_f32 v[46:47], v[46:47], v[62:63]
	v_lshlrev_b32_e32 v62, 16, v59
	v_and_b32_e32 v63, 0xffff0000, v59
	v_cvt_pk_bf16_f32 v54, v46, v47
	v_pk_mul_f32 v[46:47], v[18:19], v[62:63]
	v_lshlrev_b32_e32 v66, 16, v61
	v_pk_fma_f32 v[46:47], v[14:15], v[50:51], v[46:47]
	v_and_b32_e32 v67, 0xffff0000, v61
	v_pk_fma_f32 v[44:45], v[6:7], v[44:45], v[46:47]
	v_lshlrev_b32_e32 v46, 16, v55
	v_pk_add_f32 v[44:45], v[30:31], v[44:45]
	v_and_b32_e32 v47, 0xffff0000, v55
	v_pk_mul_f32 v[44:45], v[44:45], v[46:47]
	s_nop 0
	v_cvt_pk_bf16_f32 v55, v44, v45
	v_pk_mul_f32 v[44:45], v[20:21], v[64:65]
	s_nop 0
	v_pk_fma_f32 v[44:45], v[8:9], v[32:33], v[44:45]
	s_nop 0
	v_pk_fma_f32 v[42:43], v[0:1], v[42:43], v[44:45]
	v_lshlrev_b32_e32 v44, 16, v56
	v_pk_add_f32 v[42:43], v[24:25], v[42:43]
	v_and_b32_e32 v45, 0xffff0000, v56
	v_pk_mul_f32 v[42:43], v[42:43], v[44:45]
	s_nop 0
	v_cvt_pk_bf16_f32 v56, v42, v43
	v_pk_mul_f32 v[42:43], v[22:23], v[66:67]
	s_nop 0
	v_pk_fma_f32 v[42:43], v[10:11], v[52:53], v[42:43]
	s_nop 0
	v_pk_fma_f32 v[40:41], v[2:3], v[40:41], v[42:43]
	v_lshlrev_b32_e32 v42, 16, v57
	v_pk_add_f32 v[40:41], v[26:27], v[40:41]
	v_and_b32_e32 v43, 0xffff0000, v57
	v_pk_mul_f32 v[40:41], v[40:41], v[42:43]
	s_nop 0
	v_cvt_pk_bf16_f32 v57, v40, v41
	v_lshl_add_u64 v[40:41], v[38:39], 0, v[70:71]
	global_store_dwordx4 v[40:41], v[54:57], off offset:1024
	v_add_u32_e32 v168, s4, v69
	v_lshlrev_b64 v[70:71], 1, v[168:169]
	v_lshl_add_u64 v[44:45], v[36:37], 0, v[70:71]
	s_waitcnt vmcnt(26)
; __device__ __forceinline__ float bf_lo(unsigned u) { return __uint_as_float(u << 16); }
; __device__ __forceinline__ float bf_hi(unsigned u) { return __uint_as_float(u & 0xffff0000u); }
; __device__ __forceinline__ void conv_phase(const bf16_t* proj, bf16_t* ycat, const float* cw, const float* cb, int tid) {
;     ...
; #pragma unroll 4
;         for (int rr = 0; rr < 16; ++rr) {
;             const bf16_t* p = proj + (size_t)(row0 + rr) * 1024 + c0;
;             const u32x4 gb = *(const u32x4*)p, pc = *(const u32x4*)(p + 512);
;             float p0[8], y[8];
; #pragma unroll
;             for (int e = 0; e < 4; ++e) { p0[2 * e] = bf_lo(pc[e]); p0[2 * e + 1] = bf_hi(pc[e]); }
; #pragma unroll
;             for (int e = 0; e < 8; ++e) y[e] = w2[e] * p0[e] + w1[e] * p1[e] + w0[e] * p2[e] + bb[e];
;             u32x4 o;
; #pragma unroll
;             for (int e = 0; e < 4; ++e) o[e] = cvt_pk_bf16(bf_lo(gb[e]) * y[2 * e], bf_hi(gb[e]) * y[2 * e + 1]);
;             *(u32x4*)(ycat + (size_t)(row0 + rr) * DM + AW + c0) = o;
; #pragma unroll
;             for (int e = 0; e < 8; ++e) { p2[e] = p1[e]; p1[e] = p0[e]; }
;         }
	v_mov_b32_e32 v40, v108
	v_mov_b32_e32 v41, v109
	v_mov_b32_e32 v42, v110
	v_mov_b32_e32 v43, v111
	v_mov_b32_e32 v44, v112
	v_mov_b32_e32 v45, v113
	v_mov_b32_e32 v46, v114
	v_mov_b32_e32 v47, v115
	s_addk_i32 s4, 0x1000
	v_lshlrev_b32_e32 v60, 16, v44
	v_and_b32_e32 v61, 0xffff0000, v44
	v_pk_mul_f32 v[54:55], v[16:17], v[60:61]
	v_lshlrev_b32_e32 v58, 16, v45
	v_pk_fma_f32 v[54:55], v[12:13], v[34:35], v[54:55]
	v_and_b32_e32 v59, 0xffff0000, v45
	v_pk_fma_f32 v[48:49], v[4:5], v[48:49], v[54:55]
	v_pk_mul_f32 v[44:45], v[18:19], v[58:59]
	v_pk_add_f32 v[48:49], v[28:29], v[48:49]
	v_lshlrev_b32_e32 v54, 16, v40
	v_and_b32_e32 v55, 0xffff0000, v40
	v_pk_fma_f32 v[44:45], v[14:15], v[62:63], v[44:45]
	v_pk_mul_f32 v[48:49], v[48:49], v[54:55]
	v_pk_fma_f32 v[44:45], v[6:7], v[50:51], v[44:45]
	v_cvt_pk_bf16_f32 v40, v48, v49
	v_pk_add_f32 v[44:45], v[30:31], v[44:45]
	v_lshlrev_b32_e32 v48, 16, v41
	v_and_b32_e32 v49, 0xffff0000, v41
	v_pk_mul_f32 v[44:45], v[44:45], v[48:49]
	v_lshlrev_b32_e32 v56, 16, v46
	v_and_b32_e32 v57, 0xffff0000, v46
	v_cvt_pk_bf16_f32 v41, v44, v45
	v_pk_mul_f32 v[44:45], v[20:21], v[56:57]
	v_lshlrev_b32_e32 v54, 16, v47
	v_pk_fma_f32 v[44:45], v[8:9], v[64:65], v[44:45]
	v_and_b32_e32 v55, 0xffff0000, v47
	v_pk_fma_f32 v[32:33], v[0:1], v[32:33], v[44:45]
	v_lshlrev_b32_e32 v44, 16, v42
	v_pk_add_f32 v[32:33], v[24:25], v[32:33]
	v_and_b32_e32 v45, 0xffff0000, v42
	v_pk_mul_f32 v[32:33], v[32:33], v[44:45]
	v_lshlrev_b32_e32 v44, 16, v43
	v_cvt_pk_bf16_f32 v42, v32, v33
	v_pk_mul_f32 v[32:33], v[22:23], v[54:55]
	v_and_b32_e32 v45, 0xffff0000, v43
	v_pk_fma_f32 v[32:33], v[10:11], v[66:67], v[32:33]
	s_nop 0
	v_pk_fma_f32 v[32:33], v[2:3], v[52:53], v[32:33]
	s_nop 0
	v_pk_add_f32 v[32:33], v[26:27], v[32:33]
	s_nop 0
	v_pk_mul_f32 v[32:33], v[32:33], v[44:45]
	s_nop 0
	v_cvt_pk_bf16_f32 v43, v32, v33
	v_lshl_add_u64 v[32:33], v[38:39], 0, v[70:71]
	global_store_dwordx4 v[32:33], v[40:43], off offset:1024
	v_add_u32_e32 v32, 0x400, v168
	v_mov_b32_e32 v33, v169
	v_lshlrev_b64 v[52:53], 1, v[32:33]
	v_lshl_add_u64 v[32:33], v[36:37], 0, v[52:53]
	s_waitcnt vmcnt(25)
	v_mov_b32_e32 v48, v116
	v_mov_b32_e32 v49, v117
	v_mov_b32_e32 v50, v118
	v_mov_b32_e32 v51, v119
	v_mov_b32_e32 v70, v120
	v_mov_b32_e32 v71, v121
	v_mov_b32_e32 v72, v122
	v_mov_b32_e32 v73, v123
	v_lshlrev_b32_e32 v40, 16, v49
	v_lshlrev_b32_e32 v46, 16, v70
	v_and_b32_e32 v47, 0xffff0000, v70
	v_pk_mul_f32 v[32:33], v[16:17], v[46:47]
	v_lshlrev_b32_e32 v44, 16, v71
	v_pk_fma_f32 v[32:33], v[12:13], v[60:61], v[32:33]
	v_and_b32_e32 v45, 0xffff0000, v71
	v_pk_fma_f32 v[32:33], v[4:5], v[34:35], v[32:33]
	v_lshlrev_b32_e32 v34, 16, v48
	v_pk_add_f32 v[32:33], v[28:29], v[32:33]
	v_and_b32_e32 v35, 0xffff0000, v48
	v_pk_mul_f32 v[32:33], v[32:33], v[34:35]
	v_pk_mul_f32 v[34:35], v[18:19], v[44:45]
	v_and_b32_e32 v41, 0xffff0000, v49
	v_pk_fma_f32 v[34:35], v[14:15], v[58:59], v[34:35]
	v_lshlrev_b32_e32 v42, 16, v72
	v_pk_fma_f32 v[34:35], v[6:7], v[62:63], v[34:35]
	v_and_b32_e32 v43, 0xffff0000, v72
	v_pk_add_f32 v[34:35], v[30:31], v[34:35]
	v_cvt_pk_bf16_f32 v32, v32, v33
	v_pk_mul_f32 v[34:35], v[34:35], v[40:41]
	v_lshlrev_b32_e32 v40, 16, v50
	v_cvt_pk_bf16_f32 v33, v34, v35
	v_pk_mul_f32 v[34:35], v[20:21], v[42:43]
	v_and_b32_e32 v41, 0xffff0000, v50
	v_pk_fma_f32 v[34:35], v[8:9], v[56:57], v[34:35]
	v_lshlrev_b32_e32 v50, 16, v51
	v_pk_fma_f32 v[34:35], v[0:1], v[64:65], v[34:35]
	v_and_b32_e32 v51, 0xffff0000, v51
	v_pk_add_f32 v[34:35], v[24:25], v[34:35]
	s_nop 0
	v_pk_mul_f32 v[34:35], v[34:35], v[40:41]
	v_lshlrev_b32_e32 v40, 16, v73
	v_and_b32_e32 v41, 0xffff0000, v73
	v_pk_mul_f32 v[48:49], v[22:23], v[40:41]
	v_cvt_pk_bf16_f32 v34, v34, v35
	v_pk_fma_f32 v[48:49], v[10:11], v[54:55], v[48:49]
	s_nop 0
	v_pk_fma_f32 v[48:49], v[2:3], v[66:67], v[48:49]
	s_nop 0
	v_pk_add_f32 v[48:49], v[26:27], v[48:49]
	s_nop 0
	v_pk_mul_f32 v[48:49], v[48:49], v[50:51]
	s_nop 0
	v_cvt_pk_bf16_f32 v35, v48, v49
	v_lshl_add_u64 v[48:49], v[38:39], 0, v[52:53]
	global_store_dwordx4 v[48:49], v[32:35], off offset:1024
	s_nop 1
	v_add_u32_e32 v32, 0x800, v168
	v_mov_b32_e32 v33, v169
	v_lshlrev_b64 v[62:63], 1, v[32:33]
	v_lshl_add_u64 v[48:49], v[36:37], 0, v[62:63]
	s_waitcnt vmcnt(24)
	v_mov_b32_e32 v32, v124
	v_mov_b32_e32 v33, v125
	v_mov_b32_e32 v34, v126
	v_mov_b32_e32 v35, v127
	v_mov_b32_e32 v50, v128
	v_mov_b32_e32 v51, v129
	v_mov_b32_e32 v52, v130
	v_mov_b32_e32 v53, v131
	v_add_u32_e32 v168, 0xc00, v168
	v_lshlrev_b64 v[70:71], 1, v[168:169]
	v_lshlrev_b32_e32 v48, 16, v50
	v_and_b32_e32 v49, 0xffff0000, v50
	v_pk_mul_f32 v[64:65], v[16:17], v[48:49]
	v_lshlrev_b32_e32 v50, 16, v51
	v_pk_fma_f32 v[64:65], v[12:13], v[46:47], v[64:65]
	v_and_b32_e32 v51, 0xffff0000, v51
	v_pk_fma_f32 v[60:61], v[4:5], v[60:61], v[64:65]
	v_lshlrev_b32_e32 v64, 16, v32
	v_pk_add_f32 v[60:61], v[28:29], v[60:61]
	v_and_b32_e32 v65, 0xffff0000, v32
	v_pk_mul_f32 v[60:61], v[60:61], v[64:65]
	v_lshlrev_b32_e32 v32, 16, v33
	v_cvt_pk_bf16_f32 v64, v60, v61
	v_pk_mul_f32 v[60:61], v[18:19], v[50:51]
	v_and_b32_e32 v33, 0xffff0000, v33
	v_pk_fma_f32 v[60:61], v[14:15], v[44:45], v[60:61]
	s_nop 0
	v_pk_fma_f32 v[58:59], v[6:7], v[58:59], v[60:61]
	s_nop 0
	v_pk_add_f32 v[58:59], v[30:31], v[58:59]
	s_nop 0
	v_pk_mul_f32 v[32:33], v[58:59], v[32:33]
	s_nop 0
	v_cvt_pk_bf16_f32 v65, v32, v33
	v_lshlrev_b32_e32 v32, 16, v52
	v_and_b32_e32 v33, 0xffff0000, v52
	v_pk_mul_f32 v[58:59], v[20:21], v[32:33]
	v_lshlrev_b32_e32 v52, 16, v53
	v_pk_fma_f32 v[58:59], v[8:9], v[42:43], v[58:59]
	v_and_b32_e32 v53, 0xffff0000, v53
	v_pk_fma_f32 v[56:57], v[0:1], v[56:57], v[58:59]
	v_lshlrev_b32_e32 v58, 16, v34
	v_pk_add_f32 v[56:57], v[24:25], v[56:57]
	v_and_b32_e32 v59, 0xffff0000, v34
	v_pk_mul_f32 v[56:57], v[56:57], v[58:59]
	v_lshlrev_b32_e32 v34, 16, v35
	v_cvt_pk_bf16_f32 v66, v56, v57
	v_pk_mul_f32 v[56:57], v[22:23], v[52:53]
	v_and_b32_e32 v35, 0xffff0000, v35
	v_pk_fma_f32 v[56:57], v[10:11], v[40:41], v[56:57]
	s_nop 0
	v_pk_fma_f32 v[54:55], v[2:3], v[54:55], v[56:57]
	s_nop 0
	v_pk_add_f32 v[54:55], v[26:27], v[54:55]
	s_nop 0
	v_pk_mul_f32 v[34:35], v[54:55], v[34:35]
	s_nop 0
	v_cvt_pk_bf16_f32 v67, v34, v35
	v_lshl_add_u64 v[34:35], v[38:39], 0, v[62:63]
	global_store_dwordx4 v[34:35], v[64:67], off offset:1024
	v_lshl_add_u64 v[34:35], v[36:37], 0, v[70:71]
	s_waitcnt vmcnt(23)
; __device__ __forceinline__ float bf_lo(unsigned u) { return __uint_as_float(u << 16); }
; __device__ __forceinline__ float bf_hi(unsigned u) { return __uint_as_float(u & 0xffff0000u); }
; __device__ __forceinline__ void conv_phase(const bf16_t* proj, bf16_t* ycat, const float* cw, const float* cb, int tid) {
;     ...
; #pragma unroll 4
;         for (int rr = 0; rr < 16; ++rr) {
;             const bf16_t* p = proj + (size_t)(row0 + rr) * 1024 + c0;
;             const u32x4 gb = *(const u32x4*)p, pc = *(const u32x4*)(p + 512);
;             float p0[8], y[8];
; #pragma unroll
;             for (int e = 0; e < 4; ++e) { p0[2 * e] = bf_lo(pc[e]); p0[2 * e + 1] = bf_hi(pc[e]); }
; #pragma unroll
;             for (int e = 0; e < 8; ++e) y[e] = w2[e] * p0[e] + w1[e] * p1[e] + w0[e] * p2[e] + bb[e];
;             u32x4 o;
; #pragma unroll
;             for (int e = 0; e < 4; ++e) o[e] = cvt_pk_bf16(bf_lo(gb[e]) * y[2 * e], bf_hi(gb[e]) * y[2 * e + 1]);
;             *(u32x4*)(ycat + (size_t)(row0 + rr) * DM + AW + c0) = o;
; #pragma unroll
;             for (int e = 0; e < 8; ++e) { p2[e] = p1[e]; p1[e] = p0[e]; }
;         }
	v_mov_b32_e32 v54, v132
	v_mov_b32_e32 v55, v133
	v_mov_b32_e32 v56, v134
	v_mov_b32_e32 v57, v135
	v_mov_b32_e32 v58, v138
	v_mov_b32_e32 v59, v139
	v_mov_b32_e32 v60, v140
	v_mov_b32_e32 v61, v141
	v_lshlrev_b32_e32 v34, 16, v58
	v_and_b32_e32 v35, 0xffff0000, v58
	v_pk_mul_f32 v[62:63], v[16:17], v[34:35]
	v_lshlrev_b32_e32 v64, 16, v60
	v_pk_fma_f32 v[62:63], v[12:13], v[48:49], v[62:63]
	v_and_b32_e32 v65, 0xffff0000, v60
	v_pk_fma_f32 v[46:47], v[4:5], v[46:47], v[62:63]
	v_lshlrev_b32_e32 v62, 16, v54
	v_pk_add_f32 v[46:47], v[28:29], v[46:47]
	v_and_b32_e32 v63, 0xffff0000, v54
	v_pk_mul_f32 v[46:47], v[46:47], v[62:63]
	v_lshlrev_b32_e32 v62, 16, v59
	v_and_b32_e32 v63, 0xffff0000, v59
	v_cvt_pk_bf16_f32 v54, v46, v47
	v_pk_mul_f32 v[46:47], v[18:19], v[62:63]
	v_lshlrev_b32_e32 v66, 16, v61
	v_pk_fma_f32 v[46:47], v[14:15], v[50:51], v[46:47]
	v_and_b32_e32 v67, 0xffff0000, v61
	v_pk_fma_f32 v[44:45], v[6:7], v[44:45], v[46:47]
	v_lshlrev_b32_e32 v46, 16, v55
	v_pk_add_f32 v[44:45], v[30:31], v[44:45]
	v_and_b32_e32 v47, 0xffff0000, v55
	v_pk_mul_f32 v[44:45], v[44:45], v[46:47]
	s_nop 0
	v_cvt_pk_bf16_f32 v55, v44, v45
	v_pk_mul_f32 v[44:45], v[20:21], v[64:65]
	s_nop 0
	v_pk_fma_f32 v[44:45], v[8:9], v[32:33], v[44:45]
	s_nop 0
	v_pk_fma_f32 v[42:43], v[0:1], v[42:43], v[44:45]
	v_lshlrev_b32_e32 v44, 16, v56
	v_pk_add_f32 v[42:43], v[24:25], v[42:43]
	v_and_b32_e32 v45, 0xffff0000, v56
	v_pk_mul_f32 v[42:43], v[42:43], v[44:45]
	s_nop 0
	v_cvt_pk_bf16_f32 v56, v42, v43
	v_pk_mul_f32 v[42:43], v[22:23], v[66:67]
	s_nop 0
	v_pk_fma_f32 v[42:43], v[10:11], v[52:53], v[42:43]
	s_nop 0
	v_pk_fma_f32 v[40:41], v[2:3], v[40:41], v[42:43]
	v_lshlrev_b32_e32 v42, 16, v57
	v_pk_add_f32 v[40:41], v[26:27], v[40:41]
	v_and_b32_e32 v43, 0xffff0000, v57
	v_pk_mul_f32 v[40:41], v[40:41], v[42:43]
	s_nop 0
	v_cvt_pk_bf16_f32 v57, v40, v41
	v_lshl_add_u64 v[40:41], v[38:39], 0, v[70:71]
	global_store_dwordx4 v[40:41], v[54:57], off offset:1024
	v_add_u32_e32 v168, s4, v69
	v_lshlrev_b64 v[70:71], 1, v[168:169]
	v_lshl_add_u64 v[44:45], v[36:37], 0, v[70:71]
	s_waitcnt vmcnt(22)
	v_mov_b32_e32 v40, v142
	v_mov_b32_e32 v41, v143
	v_mov_b32_e32 v42, v144
	v_mov_b32_e32 v43, v145
	v_mov_b32_e32 v44, v146
	v_mov_b32_e32 v45, v147
	v_mov_b32_e32 v46, v148
	v_mov_b32_e32 v47, v149
	s_addk_i32 s4, 0x1000
	v_lshlrev_b32_e32 v60, 16, v44
	v_and_b32_e32 v61, 0xffff0000, v44
	v_pk_mul_f32 v[54:55], v[16:17], v[60:61]
	v_lshlrev_b32_e32 v58, 16, v45
	v_pk_fma_f32 v[54:55], v[12:13], v[34:35], v[54:55]
	v_and_b32_e32 v59, 0xffff0000, v45
	v_pk_fma_f32 v[48:49], v[4:5], v[48:49], v[54:55]
	v_pk_mul_f32 v[44:45], v[18:19], v[58:59]
	v_pk_add_f32 v[48:49], v[28:29], v[48:49]
	v_lshlrev_b32_e32 v54, 16, v40
	v_and_b32_e32 v55, 0xffff0000, v40
	v_pk_fma_f32 v[44:45], v[14:15], v[62:63], v[44:45]
	v_pk_mul_f32 v[48:49], v[48:49], v[54:55]
	v_pk_fma_f32 v[44:45], v[6:7], v[50:51], v[44:45]
	v_cvt_pk_bf16_f32 v40, v48, v49
	v_pk_add_f32 v[44:45], v[30:31], v[44:45]
	v_lshlrev_b32_e32 v48, 16, v41
	v_and_b32_e32 v49, 0xffff0000, v41
	v_pk_mul_f32 v[44:45], v[44:45], v[48:49]
	v_lshlrev_b32_e32 v56, 16, v46
	v_and_b32_e32 v57, 0xffff0000, v46
	v_cvt_pk_bf16_f32 v41, v44, v45
	v_pk_mul_f32 v[44:45], v[20:21], v[56:57]
	v_lshlrev_b32_e32 v54, 16, v47
	v_pk_fma_f32 v[44:45], v[8:9], v[64:65], v[44:45]
	v_and_b32_e32 v55, 0xffff0000, v47
	v_pk_fma_f32 v[32:33], v[0:1], v[32:33], v[44:45]
	v_lshlrev_b32_e32 v44, 16, v42
	v_pk_add_f32 v[32:33], v[24:25], v[32:33]
	v_and_b32_e32 v45, 0xffff0000, v42
	v_pk_mul_f32 v[32:33], v[32:33], v[44:45]
	v_lshlrev_b32_e32 v44, 16, v43
	v_cvt_pk_bf16_f32 v42, v32, v33
	v_pk_mul_f32 v[32:33], v[22:23], v[54:55]
	v_and_b32_e32 v45, 0xffff0000, v43
	v_pk_fma_f32 v[32:33], v[10:11], v[66:67], v[32:33]
	s_nop 0
	v_pk_fma_f32 v[32:33], v[2:3], v[52:53], v[32:33]
	s_nop 0
	v_pk_add_f32 v[32:33], v[26:27], v[32:33]
	s_nop 0
	v_pk_mul_f32 v[32:33], v[32:33], v[44:45]
	s_nop 0
	v_cvt_pk_bf16_f32 v43, v32, v33
	v_lshl_add_u64 v[32:33], v[38:39], 0, v[70:71]
	global_store_dwordx4 v[32:33], v[40:43], off offset:1024
	v_add_u32_e32 v32, 0x400, v168
	v_mov_b32_e32 v33, v169
	v_lshlrev_b64 v[52:53], 1, v[32:33]
	v_lshl_add_u64 v[32:33], v[36:37], 0, v[52:53]
	s_waitcnt vmcnt(21)
	v_mov_b32_e32 v48, v150
	v_mov_b32_e32 v49, v151
	v_mov_b32_e32 v50, v152
	v_mov_b32_e32 v51, v153
	v_mov_b32_e32 v70, v154
	v_mov_b32_e32 v71, v155
	v_mov_b32_e32 v72, v156
	v_mov_b32_e32 v73, v157
	v_lshlrev_b32_e32 v40, 16, v49
	v_lshlrev_b32_e32 v46, 16, v70
	v_and_b32_e32 v47, 0xffff0000, v70
	v_pk_mul_f32 v[32:33], v[16:17], v[46:47]
	v_lshlrev_b32_e32 v44, 16, v71
	v_pk_fma_f32 v[32:33], v[12:13], v[60:61], v[32:33]
	v_and_b32_e32 v45, 0xffff0000, v71
	v_pk_fma_f32 v[32:33], v[4:5], v[34:35], v[32:33]
	v_lshlrev_b32_e32 v34, 16, v48
	v_pk_add_f32 v[32:33], v[28:29], v[32:33]
	v_and_b32_e32 v35, 0xffff0000, v48
	v_pk_mul_f32 v[32:33], v[32:33], v[34:35]
	v_pk_mul_f32 v[34:35], v[18:19], v[44:45]
	v_and_b32_e32 v41, 0xffff0000, v49
	v_pk_fma_f32 v[34:35], v[14:15], v[58:59], v[34:35]
	v_lshlrev_b32_e32 v42, 16, v72
	v_pk_fma_f32 v[34:35], v[6:7], v[62:63], v[34:35]
	v_and_b32_e32 v43, 0xffff0000, v72
	v_pk_add_f32 v[34:35], v[30:31], v[34:35]
	v_cvt_pk_bf16_f32 v32, v32, v33
	v_pk_mul_f32 v[34:35], v[34:35], v[40:41]
	v_lshlrev_b32_e32 v40, 16, v50
	v_cvt_pk_bf16_f32 v33, v34, v35
	v_pk_mul_f32 v[34:35], v[20:21], v[42:43]
	v_and_b32_e32 v41, 0xffff0000, v50
	v_pk_fma_f32 v[34:35], v[8:9], v[56:57], v[34:35]
	v_lshlrev_b32_e32 v50, 16, v51
	v_pk_fma_f32 v[34:35], v[0:1], v[64:65], v[34:35]
	v_and_b32_e32 v51, 0xffff0000, v51
	v_pk_add_f32 v[34:35], v[24:25], v[34:35]
	s_nop 0
	v_pk_mul_f32 v[34:35], v[34:35], v[40:41]
	v_lshlrev_b32_e32 v40, 16, v73
	v_and_b32_e32 v41, 0xffff0000, v73
	v_pk_mul_f32 v[48:49], v[22:23], v[40:41]
	v_cvt_pk_bf16_f32 v34, v34, v35
	v_pk_fma_f32 v[48:49], v[10:11], v[54:55], v[48:49]
	s_nop 0
	v_pk_fma_f32 v[48:49], v[2:3], v[66:67], v[48:49]
	s_nop 0
	v_pk_add_f32 v[48:49], v[26:27], v[48:49]
	s_nop 0
	v_pk_mul_f32 v[48:49], v[48:49], v[50:51]
	s_nop 0
	v_cvt_pk_bf16_f32 v35, v48, v49
	v_lshl_add_u64 v[48:49], v[38:39], 0, v[52:53]
	global_store_dwordx4 v[48:49], v[32:35], off offset:1024
	s_nop 1
	v_add_u32_e32 v32, 0x800, v168
	v_mov_b32_e32 v33, v169
	v_lshlrev_b64 v[62:63], 1, v[32:33]
	v_lshl_add_u64 v[48:49], v[36:37], 0, v[62:63]
	s_waitcnt vmcnt(20)
; __device__ __forceinline__ float bf_lo(unsigned u) { return __uint_as_float(u << 16); }
; __device__ __forceinline__ float bf_hi(unsigned u) { return __uint_as_float(u & 0xffff0000u); }
; __device__ __forceinline__ void conv_phase(const bf16_t* proj, bf16_t* ycat, const float* cw, const float* cb, int tid) {
;     ...
; #pragma unroll 4
;         for (int rr = 0; rr < 16; ++rr) {
;             const bf16_t* p = proj + (size_t)(row0 + rr) * 1024 + c0;
;             const u32x4 gb = *(const u32x4*)p, pc = *(const u32x4*)(p + 512);
;             float p0[8], y[8];
; #pragma unroll
;             for (int e = 0; e < 4; ++e) { p0[2 * e] = bf_lo(pc[e]); p0[2 * e + 1] = bf_hi(pc[e]); }
; #pragma unroll
;             for (int e = 0; e < 8; ++e) y[e] = w2[e] * p0[e] + w1[e] * p1[e] + w0[e] * p2[e] + bb[e];
;             u32x4 o;
; #pragma unroll
;             for (int e = 0; e < 4; ++e) o[e] = cvt_pk_bf16(bf_lo(gb[e]) * y[2 * e], bf_hi(gb[e]) * y[2 * e + 1]);
;             *(u32x4*)(ycat + (size_t)(row0 + rr) * DM + AW + c0) = o;
; #pragma unroll
;             for (int e = 0; e < 8; ++e) { p2[e] = p1[e]; p1[e] = p0[e]; }
;         }
	v_mov_b32_e32 v32, v158
	v_mov_b32_e32 v33, v159
	v_mov_b32_e32 v34, v160
	v_mov_b32_e32 v35, v161
	v_mov_b32_e32 v50, v162
	v_mov_b32_e32 v51, v163
	v_mov_b32_e32 v52, v164
	v_mov_b32_e32 v53, v165
	v_add_u32_e32 v168, 0xc00, v168
	v_lshlrev_b64 v[70:71], 1, v[168:169]
	v_lshlrev_b32_e32 v48, 16, v50
	v_and_b32_e32 v49, 0xffff0000, v50
	v_pk_mul_f32 v[64:65], v[16:17], v[48:49]
	v_lshlrev_b32_e32 v50, 16, v51
	v_pk_fma_f32 v[64:65], v[12:13], v[46:47], v[64:65]
	v_and_b32_e32 v51, 0xffff0000, v51
	v_pk_fma_f32 v[60:61], v[4:5], v[60:61], v[64:65]
	v_lshlrev_b32_e32 v64, 16, v32
	v_pk_add_f32 v[60:61], v[28:29], v[60:61]
	v_and_b32_e32 v65, 0xffff0000, v32
	v_pk_mul_f32 v[60:61], v[60:61], v[64:65]
	v_lshlrev_b32_e32 v32, 16, v33
	v_cvt_pk_bf16_f32 v64, v60, v61
	v_pk_mul_f32 v[60:61], v[18:19], v[50:51]
	v_and_b32_e32 v33, 0xffff0000, v33
	v_pk_fma_f32 v[60:61], v[14:15], v[44:45], v[60:61]
	s_nop 0
	v_pk_fma_f32 v[58:59], v[6:7], v[58:59], v[60:61]
	s_nop 0
	v_pk_add_f32 v[58:59], v[30:31], v[58:59]
	s_nop 0
	v_pk_mul_f32 v[32:33], v[58:59], v[32:33]
	s_nop 0
	v_cvt_pk_bf16_f32 v65, v32, v33
	v_lshlrev_b32_e32 v32, 16, v52
	v_and_b32_e32 v33, 0xffff0000, v52
	v_pk_mul_f32 v[58:59], v[20:21], v[32:33]
	v_lshlrev_b32_e32 v52, 16, v53
	v_pk_fma_f32 v[58:59], v[8:9], v[42:43], v[58:59]
	v_and_b32_e32 v53, 0xffff0000, v53
	v_pk_fma_f32 v[56:57], v[0:1], v[56:57], v[58:59]
	v_lshlrev_b32_e32 v58, 16, v34
	v_pk_add_f32 v[56:57], v[24:25], v[56:57]
	v_and_b32_e32 v59, 0xffff0000, v34
	v_pk_mul_f32 v[56:57], v[56:57], v[58:59]
	v_lshlrev_b32_e32 v34, 16, v35
	v_cvt_pk_bf16_f32 v66, v56, v57
	v_pk_mul_f32 v[56:57], v[22:23], v[52:53]
	v_and_b32_e32 v35, 0xffff0000, v35
	v_pk_fma_f32 v[56:57], v[10:11], v[40:41], v[56:57]
	s_nop 0
	v_pk_fma_f32 v[54:55], v[2:3], v[54:55], v[56:57]
	s_nop 0
	v_pk_add_f32 v[54:55], v[26:27], v[54:55]
	s_nop 0
	v_pk_mul_f32 v[34:35], v[54:55], v[34:35]
	s_nop 0
	v_cvt_pk_bf16_f32 v67, v34, v35
	v_lshl_add_u64 v[34:35], v[38:39], 0, v[62:63]
	global_store_dwordx4 v[34:35], v[64:67], off offset:1024
	v_lshl_add_u64 v[34:35], v[36:37], 0, v[70:71]
	s_waitcnt vmcnt(19)
	v_mov_b32_e32 v54, v186
	v_mov_b32_e32 v55, v187
	v_mov_b32_e32 v56, v188
	v_mov_b32_e32 v57, v189
	v_mov_b32_e32 v58, v190
	v_mov_b32_e32 v59, v191
	v_mov_b32_e32 v60, v192
	v_mov_b32_e32 v61, v193
	v_lshlrev_b32_e32 v34, 16, v58
	v_and_b32_e32 v35, 0xffff0000, v58
	v_pk_mul_f32 v[62:63], v[16:17], v[34:35]
	v_lshlrev_b32_e32 v64, 16, v60
	v_pk_fma_f32 v[62:63], v[12:13], v[48:49], v[62:63]
	v_and_b32_e32 v65, 0xffff0000, v60
	v_pk_fma_f32 v[46:47], v[4:5], v[46:47], v[62:63]
	v_lshlrev_b32_e32 v62, 16, v54
	v_pk_add_f32 v[46:47], v[28:29], v[46:47]
	v_and_b32_e32 v63, 0xffff0000, v54
	v_pk_mul_f32 v[46:47], v[46:47], v[62:63]
	v_lshlrev_b32_e32 v62, 16, v59
	v_and_b32_e32 v63, 0xffff0000, v59
	v_cvt_pk_bf16_f32 v54, v46, v47
	v_pk_mul_f32 v[46:47], v[18:19], v[62:63]
	v_lshlrev_b32_e32 v66, 16, v61
	v_pk_fma_f32 v[46:47], v[14:15], v[50:51], v[46:47]
	v_and_b32_e32 v67, 0xffff0000, v61
	v_pk_fma_f32 v[44:45], v[6:7], v[44:45], v[46:47]
	v_lshlrev_b32_e32 v46, 16, v55
	v_pk_add_f32 v[44:45], v[30:31], v[44:45]
	v_and_b32_e32 v47, 0xffff0000, v55
	v_pk_mul_f32 v[44:45], v[44:45], v[46:47]
	s_nop 0
	v_cvt_pk_bf16_f32 v55, v44, v45
	v_pk_mul_f32 v[44:45], v[20:21], v[64:65]
	s_nop 0
	v_pk_fma_f32 v[44:45], v[8:9], v[32:33], v[44:45]
	s_nop 0
	v_pk_fma_f32 v[42:43], v[0:1], v[42:43], v[44:45]
	v_lshlrev_b32_e32 v44, 16, v56
	v_pk_add_f32 v[42:43], v[24:25], v[42:43]
	v_and_b32_e32 v45, 0xffff0000, v56
	v_pk_mul_f32 v[42:43], v[42:43], v[44:45]
	s_nop 0
	v_cvt_pk_bf16_f32 v56, v42, v43
	v_pk_mul_f32 v[42:43], v[22:23], v[66:67]
	s_nop 0
	v_pk_fma_f32 v[42:43], v[10:11], v[52:53], v[42:43]
	s_nop 0
	v_pk_fma_f32 v[40:41], v[2:3], v[40:41], v[42:43]
	v_lshlrev_b32_e32 v42, 16, v57
	v_pk_add_f32 v[40:41], v[26:27], v[40:41]
	v_and_b32_e32 v43, 0xffff0000, v57
	v_pk_mul_f32 v[40:41], v[40:41], v[42:43]
	s_nop 0
	v_cvt_pk_bf16_f32 v57, v40, v41
	v_lshl_add_u64 v[40:41], v[38:39], 0, v[70:71]
	global_store_dwordx4 v[40:41], v[54:57], off offset:1024
	v_add_u32_e32 v168, s4, v69
	v_lshlrev_b64 v[70:71], 1, v[168:169]
	v_lshl_add_u64 v[44:45], v[36:37], 0, v[70:71]
	s_waitcnt vmcnt(18)
	v_mov_b32_e32 v40, v194
	v_mov_b32_e32 v41, v195
	v_mov_b32_e32 v42, v196
	v_mov_b32_e32 v43, v197
	v_mov_b32_e32 v44, v198
	v_mov_b32_e32 v45, v199
	v_mov_b32_e32 v46, v200
	v_mov_b32_e32 v47, v201
	s_addk_i32 s4, 0x1000
	v_lshlrev_b32_e32 v60, 16, v44
	v_and_b32_e32 v61, 0xffff0000, v44
	v_pk_mul_f32 v[54:55], v[16:17], v[60:61]
	v_lshlrev_b32_e32 v58, 16, v45
	v_pk_fma_f32 v[54:55], v[12:13], v[34:35], v[54:55]
	v_and_b32_e32 v59, 0xffff0000, v45
	v_pk_fma_f32 v[48:49], v[4:5], v[48:49], v[54:55]
	v_pk_mul_f32 v[44:45], v[18:19], v[58:59]
	v_pk_add_f32 v[48:49], v[28:29], v[48:49]
	v_lshlrev_b32_e32 v54, 16, v40
	v_and_b32_e32 v55, 0xffff0000, v40
	v_pk_fma_f32 v[44:45], v[14:15], v[62:63], v[44:45]
	v_pk_mul_f32 v[48:49], v[48:49], v[54:55]
	v_pk_fma_f32 v[44:45], v[6:7], v[50:51], v[44:45]
	v_cvt_pk_bf16_f32 v40, v48, v49
	v_pk_add_f32 v[44:45], v[30:31], v[44:45]
	v_lshlrev_b32_e32 v48, 16, v41
	v_and_b32_e32 v49, 0xffff0000, v41
	v_pk_mul_f32 v[44:45], v[44:45], v[48:49]
	v_lshlrev_b32_e32 v56, 16, v46
	v_and_b32_e32 v57, 0xffff0000, v46
	v_cvt_pk_bf16_f32 v41, v44, v45
	v_pk_mul_f32 v[44:45], v[20:21], v[56:57]
	v_lshlrev_b32_e32 v54, 16, v47
	v_pk_fma_f32 v[44:45], v[8:9], v[64:65], v[44:45]
	v_and_b32_e32 v55, 0xffff0000, v47
	v_pk_fma_f32 v[32:33], v[0:1], v[32:33], v[44:45]
	v_lshlrev_b32_e32 v44, 16, v42
	v_pk_add_f32 v[32:33], v[24:25], v[32:33]
	v_and_b32_e32 v45, 0xffff0000, v42
	v_pk_mul_f32 v[32:33], v[32:33], v[44:45]
	v_lshlrev_b32_e32 v44, 16, v43
	v_cvt_pk_bf16_f32 v42, v32, v33
	v_pk_mul_f32 v[32:33], v[22:23], v[54:55]
	v_and_b32_e32 v45, 0xffff0000, v43
	v_pk_fma_f32 v[32:33], v[10:11], v[66:67], v[32:33]
	s_nop 0
	v_pk_fma_f32 v[32:33], v[2:3], v[52:53], v[32:33]
	s_nop 0
	v_pk_add_f32 v[32:33], v[26:27], v[32:33]
	s_nop 0
	v_pk_mul_f32 v[32:33], v[32:33], v[44:45]
	s_nop 0
	v_cvt_pk_bf16_f32 v43, v32, v33
	v_lshl_add_u64 v[32:33], v[38:39], 0, v[70:71]
	global_store_dwordx4 v[32:33], v[40:43], off offset:1024
	v_add_u32_e32 v32, 0x400, v168
	v_mov_b32_e32 v33, v169
	v_lshlrev_b64 v[52:53], 1, v[32:33]
	v_lshl_add_u64 v[32:33], v[36:37], 0, v[52:53]
	s_waitcnt vmcnt(17)
; __device__ __forceinline__ float bf_lo(unsigned u) { return __uint_as_float(u << 16); }
; __device__ __forceinline__ float bf_hi(unsigned u) { return __uint_as_float(u & 0xffff0000u); }
; __device__ __forceinline__ void conv_phase(const bf16_t* proj, bf16_t* ycat, const float* cw, const float* cb, int tid) {
;     ...
; #pragma unroll 4
;         for (int rr = 0; rr < 16; ++rr) {
;             const bf16_t* p = proj + (size_t)(row0 + rr) * 1024 + c0;
;             const u32x4 gb = *(const u32x4*)p, pc = *(const u32x4*)(p + 512);
;             float p0[8], y[8];
; #pragma unroll
;             for (int e = 0; e < 4; ++e) { p0[2 * e] = bf_lo(pc[e]); p0[2 * e + 1] = bf_hi(pc[e]); }
; #pragma unroll
;             for (int e = 0; e < 8; ++e) y[e] = w2[e] * p0[e] + w1[e] * p1[e] + w0[e] * p2[e] + bb[e];
;             u32x4 o;
; #pragma unroll
;             for (int e = 0; e < 4; ++e) o[e] = cvt_pk_bf16(bf_lo(gb[e]) * y[2 * e], bf_hi(gb[e]) * y[2 * e + 1]);
;             *(u32x4*)(ycat + (size_t)(row0 + rr) * DM + AW + c0) = o;
; #pragma unroll
;             for (int e = 0; e < 8; ++e) { p2[e] = p1[e]; p1[e] = p0[e]; }
;         }
	v_mov_b32_e32 v48, v202
	v_mov_b32_e32 v49, v203
	v_mov_b32_e32 v50, v204
	v_mov_b32_e32 v51, v205
	v_mov_b32_e32 v70, v206
	v_mov_b32_e32 v71, v207
	v_mov_b32_e32 v72, v208
	v_mov_b32_e32 v73, v209
	v_lshlrev_b32_e32 v40, 16, v49
	v_lshlrev_b32_e32 v46, 16, v70
	v_and_b32_e32 v47, 0xffff0000, v70
	v_pk_mul_f32 v[32:33], v[16:17], v[46:47]
	v_lshlrev_b32_e32 v44, 16, v71
	v_pk_fma_f32 v[32:33], v[12:13], v[60:61], v[32:33]
	v_and_b32_e32 v45, 0xffff0000, v71
	v_pk_fma_f32 v[32:33], v[4:5], v[34:35], v[32:33]
	v_lshlrev_b32_e32 v34, 16, v48
	v_pk_add_f32 v[32:33], v[28:29], v[32:33]
	v_and_b32_e32 v35, 0xffff0000, v48
	v_pk_mul_f32 v[32:33], v[32:33], v[34:35]
	v_pk_mul_f32 v[34:35], v[18:19], v[44:45]
	v_and_b32_e32 v41, 0xffff0000, v49
	v_pk_fma_f32 v[34:35], v[14:15], v[58:59], v[34:35]
	v_lshlrev_b32_e32 v42, 16, v72
	v_pk_fma_f32 v[34:35], v[6:7], v[62:63], v[34:35]
	v_and_b32_e32 v43, 0xffff0000, v72
	v_pk_add_f32 v[34:35], v[30:31], v[34:35]
	v_cvt_pk_bf16_f32 v32, v32, v33
	v_pk_mul_f32 v[34:35], v[34:35], v[40:41]
	v_lshlrev_b32_e32 v40, 16, v50
	v_cvt_pk_bf16_f32 v33, v34, v35
	v_pk_mul_f32 v[34:35], v[20:21], v[42:43]
	v_and_b32_e32 v41, 0xffff0000, v50
	v_pk_fma_f32 v[34:35], v[8:9], v[56:57], v[34:35]
	v_lshlrev_b32_e32 v50, 16, v51
	v_pk_fma_f32 v[34:35], v[0:1], v[64:65], v[34:35]
	v_and_b32_e32 v51, 0xffff0000, v51
	v_pk_add_f32 v[34:35], v[24:25], v[34:35]
	s_nop 0
	v_pk_mul_f32 v[34:35], v[34:35], v[40:41]
	v_lshlrev_b32_e32 v40, 16, v73
	v_and_b32_e32 v41, 0xffff0000, v73
	v_pk_mul_f32 v[48:49], v[22:23], v[40:41]
	v_cvt_pk_bf16_f32 v34, v34, v35
	v_pk_fma_f32 v[48:49], v[10:11], v[54:55], v[48:49]
	s_nop 0
	v_pk_fma_f32 v[48:49], v[2:3], v[66:67], v[48:49]
	s_nop 0
	v_pk_add_f32 v[48:49], v[26:27], v[48:49]
	s_nop 0
	v_pk_mul_f32 v[48:49], v[48:49], v[50:51]
	s_nop 0
	v_cvt_pk_bf16_f32 v35, v48, v49
	v_lshl_add_u64 v[48:49], v[38:39], 0, v[52:53]
	global_store_dwordx4 v[48:49], v[32:35], off offset:1024
	s_nop 1
	v_add_u32_e32 v32, 0x800, v168
	v_mov_b32_e32 v33, v169
	v_lshlrev_b64 v[62:63], 1, v[32:33]
	v_lshl_add_u64 v[48:49], v[36:37], 0, v[62:63]
	s_waitcnt vmcnt(16)
	v_mov_b32_e32 v32, v210
	v_mov_b32_e32 v33, v211
	v_mov_b32_e32 v34, v212
	v_mov_b32_e32 v35, v213
	v_mov_b32_e32 v50, v214
	v_mov_b32_e32 v51, v215
	v_mov_b32_e32 v52, v216
	v_mov_b32_e32 v53, v217
	v_add_u32_e32 v168, 0xc00, v168
	v_lshlrev_b64 v[70:71], 1, v[168:169]
	v_lshlrev_b32_e32 v48, 16, v50
	v_and_b32_e32 v49, 0xffff0000, v50
	v_pk_mul_f32 v[64:65], v[16:17], v[48:49]
	v_lshlrev_b32_e32 v50, 16, v51
	v_pk_fma_f32 v[64:65], v[12:13], v[46:47], v[64:65]
	v_and_b32_e32 v51, 0xffff0000, v51
	v_pk_fma_f32 v[60:61], v[4:5], v[60:61], v[64:65]
	v_lshlrev_b32_e32 v64, 16, v32
	v_pk_add_f32 v[60:61], v[28:29], v[60:61]
	v_and_b32_e32 v65, 0xffff0000, v32
	v_pk_mul_f32 v[60:61], v[60:61], v[64:65]
	v_lshlrev_b32_e32 v32, 16, v33
	v_cvt_pk_bf16_f32 v64, v60, v61
	v_pk_mul_f32 v[60:61], v[18:19], v[50:51]
	v_and_b32_e32 v33, 0xffff0000, v33
	v_pk_fma_f32 v[60:61], v[14:15], v[44:45], v[60:61]
	s_nop 0
	v_pk_fma_f32 v[58:59], v[6:7], v[58:59], v[60:61]
	s_nop 0
	v_pk_add_f32 v[58:59], v[30:31], v[58:59]
	s_nop 0
	v_pk_mul_f32 v[32:33], v[58:59], v[32:33]
	s_nop 0
	v_cvt_pk_bf16_f32 v65, v32, v33
	v_lshlrev_b32_e32 v32, 16, v52
	v_and_b32_e32 v33, 0xffff0000, v52
	v_pk_mul_f32 v[58:59], v[20:21], v[32:33]
	v_lshlrev_b32_e32 v52, 16, v53
	v_pk_fma_f32 v[58:59], v[8:9], v[42:43], v[58:59]
	v_and_b32_e32 v53, 0xffff0000, v53
	v_pk_fma_f32 v[56:57], v[0:1], v[56:57], v[58:59]
	v_lshlrev_b32_e32 v58, 16, v34
	v_pk_add_f32 v[56:57], v[24:25], v[56:57]
	v_and_b32_e32 v59, 0xffff0000, v34
	v_pk_mul_f32 v[56:57], v[56:57], v[58:59]
	v_lshlrev_b32_e32 v34, 16, v35
	v_cvt_pk_bf16_f32 v66, v56, v57
	v_pk_mul_f32 v[56:57], v[22:23], v[52:53]
	v_and_b32_e32 v35, 0xffff0000, v35
	v_pk_fma_f32 v[56:57], v[10:11], v[40:41], v[56:57]
	s_nop 0
	v_pk_fma_f32 v[54:55], v[2:3], v[54:55], v[56:57]
	s_nop 0
	v_pk_add_f32 v[54:55], v[26:27], v[54:55]
	s_nop 0
	v_pk_mul_f32 v[34:35], v[54:55], v[34:35]
	s_nop 0
	v_cvt_pk_bf16_f32 v67, v34, v35
	v_lshl_add_u64 v[34:35], v[38:39], 0, v[62:63]
	global_store_dwordx4 v[34:35], v[64:67], off offset:1024
	v_lshl_add_u64 v[34:35], v[36:37], 0, v[70:71]
	s_waitcnt vmcnt(15)
	v_mov_b32_e32 v54, v218
	v_mov_b32_e32 v55, v219
	v_mov_b32_e32 v56, v220
	v_mov_b32_e32 v57, v221
	v_mov_b32_e32 v58, v230
	v_mov_b32_e32 v59, v231
	v_mov_b32_e32 v60, v232
	v_mov_b32_e32 v61, v233
	v_lshlrev_b32_e32 v34, 16, v58
	v_and_b32_e32 v35, 0xffff0000, v58
	v_pk_mul_f32 v[62:63], v[16:17], v[34:35]
	v_lshlrev_b32_e32 v64, 16, v60
	v_pk_fma_f32 v[62:63], v[12:13], v[48:49], v[62:63]
	v_and_b32_e32 v65, 0xffff0000, v60
	v_pk_fma_f32 v[46:47], v[4:5], v[46:47], v[62:63]
	v_lshlrev_b32_e32 v62, 16, v54
	v_pk_add_f32 v[46:47], v[28:29], v[46:47]
	v_and_b32_e32 v63, 0xffff0000, v54
	v_pk_mul_f32 v[46:47], v[46:47], v[62:63]
	v_lshlrev_b32_e32 v62, 16, v59
	v_and_b32_e32 v63, 0xffff0000, v59
	v_cvt_pk_bf16_f32 v54, v46, v47
	v_pk_mul_f32 v[46:47], v[18:19], v[62:63]
	v_lshlrev_b32_e32 v66, 16, v61
	v_pk_fma_f32 v[46:47], v[14:15], v[50:51], v[46:47]
	v_and_b32_e32 v67, 0xffff0000, v61
	v_pk_fma_f32 v[44:45], v[6:7], v[44:45], v[46:47]
	v_lshlrev_b32_e32 v46, 16, v55
	v_pk_add_f32 v[44:45], v[30:31], v[44:45]
	v_and_b32_e32 v47, 0xffff0000, v55
	v_pk_mul_f32 v[44:45], v[44:45], v[46:47]
	s_nop 0
	v_cvt_pk_bf16_f32 v55, v44, v45
	v_pk_mul_f32 v[44:45], v[20:21], v[64:65]
	s_nop 0
	v_pk_fma_f32 v[44:45], v[8:9], v[32:33], v[44:45]
	s_nop 0
	v_pk_fma_f32 v[42:43], v[0:1], v[42:43], v[44:45]
	v_lshlrev_b32_e32 v44, 16, v56
	v_pk_add_f32 v[42:43], v[24:25], v[42:43]
	v_and_b32_e32 v45, 0xffff0000, v56
	v_pk_mul_f32 v[42:43], v[42:43], v[44:45]
	s_nop 0
	v_cvt_pk_bf16_f32 v56, v42, v43
	v_pk_mul_f32 v[42:43], v[22:23], v[66:67]
	s_nop 0
	v_pk_fma_f32 v[42:43], v[10:11], v[52:53], v[42:43]
	s_nop 0
	v_pk_fma_f32 v[40:41], v[2:3], v[40:41], v[42:43]
	v_lshlrev_b32_e32 v42, 16, v57
	v_pk_add_f32 v[40:41], v[26:27], v[40:41]
	v_and_b32_e32 v43, 0xffff0000, v57
	v_pk_mul_f32 v[40:41], v[40:41], v[42:43]
	s_nop 0
	v_cvt_pk_bf16_f32 v57, v40, v41
	v_lshl_add_u64 v[40:41], v[38:39], 0, v[70:71]
	global_store_dwordx4 v[40:41], v[54:57], off offset:1024
	v_readlane_b32 s4, v252, 38
	s_nop 1
	v_add_u32_e32 v68, s4, v68
	s_movk_i32 s4, 0x7ff
	v_cmp_lt_u32_e32 vcc, s4, v68
	v_readlane_b32 s4, v251, 32
	s_or_b64 s[2:3], vcc, s[2:3]
	s_nop 0
	v_add_u32_e32 v69, s4, v69
	s_andn2_b64 exec, exec, s[2:3]
	s_cbranch_execnz .LBB0_285
